# m7 plus: hw1 scan waves start their accumulation chains from a literal-zero C operand (no per-chunk zeroing)
# baseline (speedup 1.0000x reference)
.LBB0_862:
	s_add_i32 s47, s47, 64
	s_add_i32 s48, s48, 8
	s_add_i32 s70, s70, 1
	v_lshl_add_u64 v[166:167], v[166:167], 0, s[40:41]
	v_lshl_add_u64 v[168:169], v[168:169], 0, s[42:43]
	s_cmpk_lg_i32 s47, 0x800
	v_mov_b32_e32 v120, v207
	s_cbranch_scc0 .LBB0_823
.LBB0_863:
	s_and_saveexec_b64 s[50:51], s[10:11]
	s_cbranch_execz .LBB0_865
	v_lshlrev_b32_e32 v32, 16, v136
	v_and_b32_e32 v33, 0xffff0000, v136
	v_lshlrev_b32_e32 v34, 16, v137
	v_and_b32_e32 v35, 0xffff0000, v137
	v_lshlrev_b32_e32 v48, 16, v132
	v_and_b32_e32 v49, 0xffff0000, v132
	v_lshlrev_b32_e32 v50, 16, v133
	v_and_b32_e32 v51, 0xffff0000, v133
	v_lshlrev_b32_e32 v36, 16, v130
	v_and_b32_e32 v37, 0xffff0000, v130
	v_lshlrev_b32_e32 v38, 16, v131
	v_and_b32_e32 v39, 0xffff0000, v131
	v_lshlrev_b32_e32 v52, 16, v140
	v_and_b32_e32 v53, 0xffff0000, v140
	v_lshlrev_b32_e32 v54, 16, v141
	v_and_b32_e32 v55, 0xffff0000, v141
	v_lshlrev_b32_e32 v40, 16, v134
	v_and_b32_e32 v41, 0xffff0000, v134
	v_lshlrev_b32_e32 v42, 16, v135
	v_and_b32_e32 v43, 0xffff0000, v135
	v_lshlrev_b32_e32 v56, 16, v142
	v_and_b32_e32 v57, 0xffff0000, v142
	v_lshlrev_b32_e32 v58, 16, v143
	v_and_b32_e32 v59, 0xffff0000, v143
	v_lshlrev_b32_e32 v44, 16, v138
	v_and_b32_e32 v45, 0xffff0000, v138
	v_lshlrev_b32_e32 v46, 16, v139
	v_and_b32_e32 v47, 0xffff0000, v139
	v_lshlrev_b32_e32 v60, 16, v144
	v_and_b32_e32 v61, 0xffff0000, v144
	v_lshlrev_b32_e32 v62, 16, v145
	v_and_b32_e32 v63, 0xffff0000, v145

.LBB0_870:
	ds_read_b128 v[108:111], v181
	ds_read_b128 v[112:115], v180 offset:62464
	ds_read_b128 v[116:119], v180 offset:62496
	ds_read_b128 v[214:217], v181 offset:32
	s_waitcnt lgkmcnt(2)
	s_cmp_lg_u64 s[10:11], 0
	s_cbranch_scc0 .Lmy_c0_a0
	v_mfma_f32_32x32x16_bf16 v[32:47], v[108:111], v[112:115], v[32:47]
	s_branch .Lmy_c0j_a0
.Lmy_c0_a0:
	v_mfma_f32_32x32x16_bf16 v[32:47], v[108:111], v[112:115], 0
.Lmy_c0j_a0:
	ds_read_b128 v[108:111], v181 offset:8704
	ds_read_b128 v[218:221], v181 offset:8736
	s_waitcnt lgkmcnt(1)
	s_cmp_lg_u64 s[10:11], 0
	s_cbranch_scc0 .Lmy_c0_a1
	v_mfma_f32_32x32x16_bf16 v[48:63], v[108:111], v[112:115], v[48:63]
	s_branch .Lmy_c0j_a1
.Lmy_c0_a1:
	v_mfma_f32_32x32x16_bf16 v[48:63], v[108:111], v[112:115], 0
.Lmy_c0j_a1:
	v_mfma_f32_32x32x16_bf16 v[32:47], v[214:217], v[116:119], v[32:47]
	s_waitcnt lgkmcnt(0)
	v_mfma_f32_32x32x16_bf16 v[48:63], v[218:221], v[116:119], v[48:63]
	ds_read_b128 v[108:111], v181 offset:64
	ds_read_b128 v[112:115], v180 offset:62528
	ds_read_b128 v[116:119], v180 offset:62560
	ds_read_b128 v[214:217], v181 offset:96
	s_waitcnt lgkmcnt(2)
	v_mfma_f32_32x32x16_bf16 v[32:47], v[108:111], v[112:115], v[32:47]
	ds_read_b128 v[108:111], v181 offset:8768
	ds_read_b128 v[218:221], v181 offset:8800
	s_waitcnt lgkmcnt(1)
	v_mfma_f32_32x32x16_bf16 v[48:63], v[108:111], v[112:115], v[48:63]
	v_mfma_f32_32x32x16_bf16 v[32:47], v[214:217], v[116:119], v[32:47]
	s_waitcnt lgkmcnt(0)
	v_mfma_f32_32x32x16_bf16 v[48:63], v[218:221], v[116:119], v[48:63]
	ds_read_b128 v[108:111], v181 offset:128
	ds_read_b128 v[112:115], v180 offset:62592
	ds_read_b128 v[116:119], v180 offset:62624
	ds_read_b128 v[214:217], v181 offset:160
	s_waitcnt lgkmcnt(2)
	v_mfma_f32_32x32x16_bf16 v[32:47], v[108:111], v[112:115], v[32:47]
	ds_read_b128 v[108:111], v181 offset:8832
	ds_read_b128 v[218:221], v181 offset:8864
	s_waitcnt lgkmcnt(1)
	v_mfma_f32_32x32x16_bf16 v[48:63], v[108:111], v[112:115], v[48:63]
	v_mfma_f32_32x32x16_bf16 v[32:47], v[214:217], v[116:119], v[32:47]
	s_waitcnt lgkmcnt(0)
	v_mfma_f32_32x32x16_bf16 v[48:63], v[218:221], v[116:119], v[48:63]
	ds_read_b128 v[108:111], v181 offset:192
	ds_read_b128 v[112:115], v180 offset:62656
	ds_read_b128 v[116:119], v180 offset:62688
	ds_read_b128 v[214:217], v181 offset:224
	s_waitcnt lgkmcnt(2)
	v_mfma_f32_32x32x16_bf16 v[32:47], v[108:111], v[112:115], v[32:47]
	ds_read_b128 v[108:111], v181 offset:8896
	ds_read_b128 v[218:221], v181 offset:8928
	s_waitcnt lgkmcnt(1)
	v_mfma_f32_32x32x16_bf16 v[48:63], v[108:111], v[112:115], v[48:63]
	v_lshl_add_u64 v[112:113], v[168:169], 0, v[164:165]
	global_load_dwordx4 v[108:111], v[112:113], off
	s_nop 0
	global_load_dwordx4 v[112:115], v[112:113], off offset:-16
	v_mfma_f32_32x32x16_bf16 v[32:47], v[214:217], v[116:119], v[32:47]
	s_waitcnt lgkmcnt(0)
	v_mfma_f32_32x32x16_bf16 v[48:63], v[218:221], v[116:119], v[48:63]
	s_and_saveexec_b64 s[52:53], s[10:11]
	s_cbranch_execz .LBB0_872
	s_nop 7
	v_cvt_pk_bf16_f32 v116, v32, v33
	v_cvt_pk_bf16_f32 v117, v34, v35
	v_cvt_pk_bf16_f32 v122, v36, v37
	v_cvt_pk_bf16_f32 v123, v38, v39
	v_cvt_pk_bf16_f32 v118, v48, v49
	v_cvt_pk_bf16_f32 v119, v50, v51
	v_cvt_pk_bf16_f32 v208, v52, v53
	v_cvt_pk_bf16_f32 v209, v54, v55
	ds_write2_b64 v182, v[116:117], v[122:123] offset1:2
	ds_write2_b64 v182, v[118:119], v[208:209] offset0:8 offset1:10
	v_cvt_pk_bf16_f32 v116, v40, v41
	v_cvt_pk_bf16_f32 v117, v42, v43
	v_cvt_pk_bf16_f32 v122, v44, v45
	v_cvt_pk_bf16_f32 v123, v46, v47
	v_cvt_pk_bf16_f32 v118, v56, v57
	v_cvt_pk_bf16_f32 v119, v58, v59
	v_cvt_pk_bf16_f32 v208, v60, v61
	v_cvt_pk_bf16_f32 v209, v62, v63
	ds_write2_b64 v182, v[116:117], v[122:123] offset0:4 offset1:6
	ds_write2_b64 v182, v[118:119], v[208:209] offset0:12 offset1:14
